# ml_intra: key-side block transform rewritten with LDS weight reads double-buffered one block ahead (same FMA order)
# baseline (speedup 1.0000x reference)
.LBB0_674:
	s_and_b32 s45, s33, 0xfffffe00
	s_lshl_b32 s50, s63, 7
	s_bfe_u32 s56, s33, 0x70002
	s_or_b32 s45, s50, s45
	s_or_b32 s52, s45, s56
	s_ashr_i32 s53, s52, 31
	s_ashr_i32 s44, s33, 9
	s_lshl_b64 s[50:51], s[52:53], 10
	s_add_u32 s50, s58, s50
	s_addc_u32 s51, s59, s51
	s_ashr_i32 s45, s44, 31
	s_lshl_b64 s[54:55], s[44:45], 13
	s_lshl_b32 s44, s56, 6
	s_or_b32 s54, s54, s44
	s_add_i32 s44, 0, 0x12400
	s_waitcnt vmcnt(15)
	v_add_u32_e32 v57, s44, v65
	ds_read_b128 v[34:37], v57
	ds_read_b128 v[38:41], v57 offset:16
	ds_read_b128 v[100:103], v57 offset:32
	ds_read_b128 v[104:107], v57 offset:48
	ds_read_b128 v[206:209], v57 offset:64
	ds_read_b128 v[210:213], v57 offset:80
	ds_read_b128 v[214:217], v57 offset:96
	ds_read_b128 v[218:221], v57 offset:112
	s_waitcnt vmcnt(7)
	v_lshlrev_b32_e32 v108, 16, v2
	v_and_b32_e32 v110, 0xffff0000, v2
	v_lshlrev_b32_e32 v112, 16, v3
	v_and_b32_e32 v114, 0xffff0000, v3
	s_waitcnt lgkmcnt(4)
	v_pk_mul_f32 v[222:223], v[38:39], v[110:111] op_sel_hi:[1,0]
	v_pk_mul_f32 v[230:231], v[40:41], v[110:111] op_sel_hi:[1,0]
	v_pk_fma_f32 v[222:223], v[34:35], v[108:109], v[222:223] op_sel_hi:[1,0,1]
	v_pk_fma_f32 v[230:231], v[36:37], v[108:109], v[230:231] op_sel_hi:[1,0,1]
	v_pk_fma_f32 v[222:223], v[100:101], v[112:113], v[222:223] op_sel_hi:[1,0,1]
	v_pk_fma_f32 v[230:231], v[102:103], v[112:113], v[230:231] op_sel_hi:[1,0,1]
	v_pk_fma_f32 v[124:125], v[104:105], v[114:115], v[222:223] op_sel_hi:[1,0,1]
	v_pk_fma_f32 v[224:225], v[106:107], v[114:115], v[230:231] op_sel_hi:[1,0,1]
	v_add_u32_e32 v204, s44, v66
	ds_read_b128 v[34:37], v204
	ds_read_b128 v[38:41], v204 offset:16
	ds_read_b128 v[100:103], v204 offset:32
	ds_read_b128 v[104:107], v204 offset:48
	v_lshlrev_b32_e32 v116, 16, v4
	v_and_b32_e32 v118, 0xffff0000, v4
	v_lshlrev_b32_e32 v120, 16, v5
	v_and_b32_e32 v122, 0xffff0000, v5
	s_waitcnt lgkmcnt(4)
	v_pk_mul_f32 v[222:223], v[210:211], v[118:119] op_sel_hi:[1,0]
	v_pk_mul_f32 v[230:231], v[212:213], v[118:119] op_sel_hi:[1,0]
	v_pk_fma_f32 v[222:223], v[206:207], v[116:117], v[222:223] op_sel_hi:[1,0,1]
	v_pk_fma_f32 v[230:231], v[208:209], v[116:117], v[230:231] op_sel_hi:[1,0,1]
	v_pk_fma_f32 v[222:223], v[214:215], v[120:121], v[222:223] op_sel_hi:[1,0,1]
	v_pk_fma_f32 v[230:231], v[216:217], v[120:121], v[230:231] op_sel_hi:[1,0,1]
	v_pk_fma_f32 v[226:227], v[218:219], v[122:123], v[222:223] op_sel_hi:[1,0,1]
	v_pk_fma_f32 v[228:229], v[220:221], v[122:123], v[230:231] op_sel_hi:[1,0,1]
	v_cvt_pk_bf16_f32 v246, v124, v125
	v_cvt_pk_bf16_f32 v247, v224, v225
	v_cvt_pk_bf16_f32 v248, v226, v227
	v_cvt_pk_bf16_f32 v249, v228, v229
	ds_write_b128 v92, v[246:249]
	ds_read_b128 v[206:209], v204 offset:64
	ds_read_b128 v[210:213], v204 offset:80
	ds_read_b128 v[214:217], v204 offset:96
	ds_read_b128 v[218:221], v204 offset:112
	s_waitcnt vmcnt(6)
	v_lshlrev_b32_e32 v108, 16, v6
	v_and_b32_e32 v110, 0xffff0000, v6
	v_lshlrev_b32_e32 v112, 16, v7
	v_and_b32_e32 v114, 0xffff0000, v7
	s_waitcnt lgkmcnt(5)
	v_pk_mul_f32 v[222:223], v[38:39], v[110:111] op_sel_hi:[1,0]
	v_pk_mul_f32 v[230:231], v[40:41], v[110:111] op_sel_hi:[1,0]
	v_pk_fma_f32 v[222:223], v[34:35], v[108:109], v[222:223] op_sel_hi:[1,0,1]
	v_pk_fma_f32 v[230:231], v[36:37], v[108:109], v[230:231] op_sel_hi:[1,0,1]
	v_pk_fma_f32 v[222:223], v[100:101], v[112:113], v[222:223] op_sel_hi:[1,0,1]
	v_pk_fma_f32 v[230:231], v[102:103], v[112:113], v[230:231] op_sel_hi:[1,0,1]
	v_pk_fma_f32 v[124:125], v[104:105], v[114:115], v[222:223] op_sel_hi:[1,0,1]
	v_pk_fma_f32 v[224:225], v[106:107], v[114:115], v[230:231] op_sel_hi:[1,0,1]
	v_add_u32_e32 v57, s44, v67
	ds_read_b128 v[34:37], v57
	ds_read_b128 v[38:41], v57 offset:16
	ds_read_b128 v[100:103], v57 offset:32
	ds_read_b128 v[104:107], v57 offset:48
	v_lshlrev_b32_e32 v116, 16, v8
	v_and_b32_e32 v118, 0xffff0000, v8
	v_lshlrev_b32_e32 v120, 16, v9
	v_and_b32_e32 v122, 0xffff0000, v9
	s_waitcnt lgkmcnt(4)
	v_pk_mul_f32 v[222:223], v[210:211], v[118:119] op_sel_hi:[1,0]
	v_pk_mul_f32 v[230:231], v[212:213], v[118:119] op_sel_hi:[1,0]
	v_pk_fma_f32 v[222:223], v[206:207], v[116:117], v[222:223] op_sel_hi:[1,0,1]
	v_pk_fma_f32 v[230:231], v[208:209], v[116:117], v[230:231] op_sel_hi:[1,0,1]
	v_pk_fma_f32 v[222:223], v[214:215], v[120:121], v[222:223] op_sel_hi:[1,0,1]
	v_pk_fma_f32 v[230:231], v[216:217], v[120:121], v[230:231] op_sel_hi:[1,0,1]
	v_pk_fma_f32 v[226:227], v[218:219], v[122:123], v[222:223] op_sel_hi:[1,0,1]
	v_pk_fma_f32 v[228:229], v[220:221], v[122:123], v[230:231] op_sel_hi:[1,0,1]
	v_cvt_pk_bf16_f32 v246, v124, v125
	v_cvt_pk_bf16_f32 v247, v224, v225
	v_cvt_pk_bf16_f32 v248, v226, v227
	v_cvt_pk_bf16_f32 v249, v228, v229
	ds_write_b128 v93, v[246:249]
	ds_read_b128 v[206:209], v57 offset:64
	ds_read_b128 v[210:213], v57 offset:80
	ds_read_b128 v[214:217], v57 offset:96
	ds_read_b128 v[218:221], v57 offset:112
	s_waitcnt vmcnt(5)
	v_lshlrev_b32_e32 v108, 16, v10
	v_and_b32_e32 v110, 0xffff0000, v10
	v_lshlrev_b32_e32 v112, 16, v11
	v_and_b32_e32 v114, 0xffff0000, v11
	s_waitcnt lgkmcnt(5)
	v_pk_mul_f32 v[222:223], v[38:39], v[110:111] op_sel_hi:[1,0]
	v_pk_mul_f32 v[230:231], v[40:41], v[110:111] op_sel_hi:[1,0]
	v_pk_fma_f32 v[222:223], v[34:35], v[108:109], v[222:223] op_sel_hi:[1,0,1]
	v_pk_fma_f32 v[230:231], v[36:37], v[108:109], v[230:231] op_sel_hi:[1,0,1]
	v_pk_fma_f32 v[222:223], v[100:101], v[112:113], v[222:223] op_sel_hi:[1,0,1]
	v_pk_fma_f32 v[230:231], v[102:103], v[112:113], v[230:231] op_sel_hi:[1,0,1]
	v_pk_fma_f32 v[124:125], v[104:105], v[114:115], v[222:223] op_sel_hi:[1,0,1]
	v_pk_fma_f32 v[224:225], v[106:107], v[114:115], v[230:231] op_sel_hi:[1,0,1]
	v_add_u32_e32 v204, s44, v68
	ds_read_b128 v[34:37], v204
	ds_read_b128 v[38:41], v204 offset:16
	ds_read_b128 v[100:103], v204 offset:32
	ds_read_b128 v[104:107], v204 offset:48
	v_lshlrev_b32_e32 v116, 16, v12
	v_and_b32_e32 v118, 0xffff0000, v12
	v_lshlrev_b32_e32 v120, 16, v13
	v_and_b32_e32 v122, 0xffff0000, v13
	s_waitcnt lgkmcnt(4)
	v_pk_mul_f32 v[222:223], v[210:211], v[118:119] op_sel_hi:[1,0]
	v_pk_mul_f32 v[230:231], v[212:213], v[118:119] op_sel_hi:[1,0]
	v_pk_fma_f32 v[222:223], v[206:207], v[116:117], v[222:223] op_sel_hi:[1,0,1]
	v_pk_fma_f32 v[230:231], v[208:209], v[116:117], v[230:231] op_sel_hi:[1,0,1]
	v_pk_fma_f32 v[222:223], v[214:215], v[120:121], v[222:223] op_sel_hi:[1,0,1]
	v_pk_fma_f32 v[230:231], v[216:217], v[120:121], v[230:231] op_sel_hi:[1,0,1]
	v_pk_fma_f32 v[226:227], v[218:219], v[122:123], v[222:223] op_sel_hi:[1,0,1]
	v_pk_fma_f32 v[228:229], v[220:221], v[122:123], v[230:231] op_sel_hi:[1,0,1]
	v_cvt_pk_bf16_f32 v246, v124, v125
	v_cvt_pk_bf16_f32 v247, v224, v225
	v_cvt_pk_bf16_f32 v248, v226, v227
	v_cvt_pk_bf16_f32 v249, v228, v229
	ds_write_b128 v94, v[246:249]
	ds_read_b128 v[206:209], v204 offset:64
	ds_read_b128 v[210:213], v204 offset:80
	ds_read_b128 v[214:217], v204 offset:96
	ds_read_b128 v[218:221], v204 offset:112
	s_waitcnt vmcnt(4)
	v_lshlrev_b32_e32 v108, 16, v14
	v_and_b32_e32 v110, 0xffff0000, v14
	v_lshlrev_b32_e32 v112, 16, v15
	v_and_b32_e32 v114, 0xffff0000, v15
	s_waitcnt lgkmcnt(5)
	v_pk_mul_f32 v[222:223], v[38:39], v[110:111] op_sel_hi:[1,0]
	v_pk_mul_f32 v[230:231], v[40:41], v[110:111] op_sel_hi:[1,0]
	v_pk_fma_f32 v[222:223], v[34:35], v[108:109], v[222:223] op_sel_hi:[1,0,1]
	v_pk_fma_f32 v[230:231], v[36:37], v[108:109], v[230:231] op_sel_hi:[1,0,1]
	v_pk_fma_f32 v[222:223], v[100:101], v[112:113], v[222:223] op_sel_hi:[1,0,1]
	v_pk_fma_f32 v[230:231], v[102:103], v[112:113], v[230:231] op_sel_hi:[1,0,1]
	v_pk_fma_f32 v[124:125], v[104:105], v[114:115], v[222:223] op_sel_hi:[1,0,1]
	v_pk_fma_f32 v[224:225], v[106:107], v[114:115], v[230:231] op_sel_hi:[1,0,1]
	v_add_u32_e32 v57, s44, v69
	ds_read_b128 v[34:37], v57
	ds_read_b128 v[38:41], v57 offset:16
	ds_read_b128 v[100:103], v57 offset:32
	ds_read_b128 v[104:107], v57 offset:48
	v_lshlrev_b32_e32 v116, 16, v16
	v_and_b32_e32 v118, 0xffff0000, v16
	v_lshlrev_b32_e32 v120, 16, v17
	v_and_b32_e32 v122, 0xffff0000, v17
	s_waitcnt lgkmcnt(4)
	v_pk_mul_f32 v[222:223], v[210:211], v[118:119] op_sel_hi:[1,0]
	v_pk_mul_f32 v[230:231], v[212:213], v[118:119] op_sel_hi:[1,0]
	v_pk_fma_f32 v[222:223], v[206:207], v[116:117], v[222:223] op_sel_hi:[1,0,1]
	v_pk_fma_f32 v[230:231], v[208:209], v[116:117], v[230:231] op_sel_hi:[1,0,1]
	v_pk_fma_f32 v[222:223], v[214:215], v[120:121], v[222:223] op_sel_hi:[1,0,1]
	v_pk_fma_f32 v[230:231], v[216:217], v[120:121], v[230:231] op_sel_hi:[1,0,1]
	v_pk_fma_f32 v[226:227], v[218:219], v[122:123], v[222:223] op_sel_hi:[1,0,1]
	v_pk_fma_f32 v[228:229], v[220:221], v[122:123], v[230:231] op_sel_hi:[1,0,1]
	v_cvt_pk_bf16_f32 v246, v124, v125
	v_cvt_pk_bf16_f32 v247, v224, v225
	v_cvt_pk_bf16_f32 v248, v226, v227
	v_cvt_pk_bf16_f32 v249, v228, v229
	ds_write_b128 v95, v[246:249]
	ds_read_b128 v[206:209], v57 offset:64
	ds_read_b128 v[210:213], v57 offset:80
	ds_read_b128 v[214:217], v57 offset:96
	ds_read_b128 v[218:221], v57 offset:112
	s_waitcnt vmcnt(3)
	v_lshlrev_b32_e32 v108, 16, v18
	v_and_b32_e32 v110, 0xffff0000, v18
	v_lshlrev_b32_e32 v112, 16, v19
	v_and_b32_e32 v114, 0xffff0000, v19
	s_waitcnt lgkmcnt(5)
	v_pk_mul_f32 v[222:223], v[38:39], v[110:111] op_sel_hi:[1,0]
	v_pk_mul_f32 v[230:231], v[40:41], v[110:111] op_sel_hi:[1,0]
	v_pk_fma_f32 v[222:223], v[34:35], v[108:109], v[222:223] op_sel_hi:[1,0,1]
	v_pk_fma_f32 v[230:231], v[36:37], v[108:109], v[230:231] op_sel_hi:[1,0,1]
	v_pk_fma_f32 v[222:223], v[100:101], v[112:113], v[222:223] op_sel_hi:[1,0,1]
	v_pk_fma_f32 v[230:231], v[102:103], v[112:113], v[230:231] op_sel_hi:[1,0,1]
	v_pk_fma_f32 v[124:125], v[104:105], v[114:115], v[222:223] op_sel_hi:[1,0,1]
	v_pk_fma_f32 v[224:225], v[106:107], v[114:115], v[230:231] op_sel_hi:[1,0,1]
	v_add_u32_e32 v204, s44, v70
	ds_read_b128 v[34:37], v204
	ds_read_b128 v[38:41], v204 offset:16
	ds_read_b128 v[100:103], v204 offset:32
	ds_read_b128 v[104:107], v204 offset:48
	v_lshlrev_b32_e32 v116, 16, v20
	v_and_b32_e32 v118, 0xffff0000, v20
	v_lshlrev_b32_e32 v120, 16, v21
	v_and_b32_e32 v122, 0xffff0000, v21
	s_waitcnt lgkmcnt(4)
	v_pk_mul_f32 v[222:223], v[210:211], v[118:119] op_sel_hi:[1,0]
	v_pk_mul_f32 v[230:231], v[212:213], v[118:119] op_sel_hi:[1,0]
	v_pk_fma_f32 v[222:223], v[206:207], v[116:117], v[222:223] op_sel_hi:[1,0,1]
	v_pk_fma_f32 v[230:231], v[208:209], v[116:117], v[230:231] op_sel_hi:[1,0,1]
	v_pk_fma_f32 v[222:223], v[214:215], v[120:121], v[222:223] op_sel_hi:[1,0,1]
	v_pk_fma_f32 v[230:231], v[216:217], v[120:121], v[230:231] op_sel_hi:[1,0,1]
	v_pk_fma_f32 v[226:227], v[218:219], v[122:123], v[222:223] op_sel_hi:[1,0,1]
	v_pk_fma_f32 v[228:229], v[220:221], v[122:123], v[230:231] op_sel_hi:[1,0,1]
	v_cvt_pk_bf16_f32 v246, v124, v125
	v_cvt_pk_bf16_f32 v247, v224, v225
	v_cvt_pk_bf16_f32 v248, v226, v227
	v_cvt_pk_bf16_f32 v249, v228, v229
	ds_write_b128 v96, v[246:249]
	ds_read_b128 v[206:209], v204 offset:64
	ds_read_b128 v[210:213], v204 offset:80
	ds_read_b128 v[214:217], v204 offset:96
	ds_read_b128 v[218:221], v204 offset:112
	s_waitcnt vmcnt(2)
	v_lshlrev_b32_e32 v108, 16, v22
	v_and_b32_e32 v110, 0xffff0000, v22
	v_lshlrev_b32_e32 v112, 16, v23
	v_and_b32_e32 v114, 0xffff0000, v23
	s_waitcnt lgkmcnt(5)
	v_pk_mul_f32 v[222:223], v[38:39], v[110:111] op_sel_hi:[1,0]
	v_pk_mul_f32 v[230:231], v[40:41], v[110:111] op_sel_hi:[1,0]
	v_pk_fma_f32 v[222:223], v[34:35], v[108:109], v[222:223] op_sel_hi:[1,0,1]
	v_pk_fma_f32 v[230:231], v[36:37], v[108:109], v[230:231] op_sel_hi:[1,0,1]
	v_pk_fma_f32 v[222:223], v[100:101], v[112:113], v[222:223] op_sel_hi:[1,0,1]
	v_pk_fma_f32 v[230:231], v[102:103], v[112:113], v[230:231] op_sel_hi:[1,0,1]
	v_pk_fma_f32 v[124:125], v[104:105], v[114:115], v[222:223] op_sel_hi:[1,0,1]
	v_pk_fma_f32 v[224:225], v[106:107], v[114:115], v[230:231] op_sel_hi:[1,0,1]
	v_add_u32_e32 v57, s44, v71
	ds_read_b128 v[34:37], v57
	ds_read_b128 v[38:41], v57 offset:16
	ds_read_b128 v[100:103], v57 offset:32
	ds_read_b128 v[104:107], v57 offset:48
	v_lshlrev_b32_e32 v116, 16, v24
	v_and_b32_e32 v118, 0xffff0000, v24
	v_lshlrev_b32_e32 v120, 16, v25
	v_and_b32_e32 v122, 0xffff0000, v25
	s_waitcnt lgkmcnt(4)
	v_pk_mul_f32 v[222:223], v[210:211], v[118:119] op_sel_hi:[1,0]
	v_pk_mul_f32 v[230:231], v[212:213], v[118:119] op_sel_hi:[1,0]
	v_pk_fma_f32 v[222:223], v[206:207], v[116:117], v[222:223] op_sel_hi:[1,0,1]
	v_pk_fma_f32 v[230:231], v[208:209], v[116:117], v[230:231] op_sel_hi:[1,0,1]
	v_pk_fma_f32 v[222:223], v[214:215], v[120:121], v[222:223] op_sel_hi:[1,0,1]
	v_pk_fma_f32 v[230:231], v[216:217], v[120:121], v[230:231] op_sel_hi:[1,0,1]
	v_pk_fma_f32 v[226:227], v[218:219], v[122:123], v[222:223] op_sel_hi:[1,0,1]
	v_pk_fma_f32 v[228:229], v[220:221], v[122:123], v[230:231] op_sel_hi:[1,0,1]
	v_cvt_pk_bf16_f32 v246, v124, v125
	v_cvt_pk_bf16_f32 v247, v224, v225
	v_cvt_pk_bf16_f32 v248, v226, v227
	v_cvt_pk_bf16_f32 v249, v228, v229
	ds_write_b128 v97, v[246:249]
	ds_read_b128 v[206:209], v57 offset:64
	ds_read_b128 v[210:213], v57 offset:80
	ds_read_b128 v[214:217], v57 offset:96
	ds_read_b128 v[218:221], v57 offset:112
	s_waitcnt vmcnt(1)
	v_lshlrev_b32_e32 v108, 16, v26
	v_and_b32_e32 v110, 0xffff0000, v26
	v_lshlrev_b32_e32 v112, 16, v27
	v_and_b32_e32 v114, 0xffff0000, v27
	s_waitcnt lgkmcnt(5)
	v_pk_mul_f32 v[222:223], v[38:39], v[110:111] op_sel_hi:[1,0]
	v_pk_mul_f32 v[230:231], v[40:41], v[110:111] op_sel_hi:[1,0]
	v_pk_fma_f32 v[222:223], v[34:35], v[108:109], v[222:223] op_sel_hi:[1,0,1]
	v_pk_fma_f32 v[230:231], v[36:37], v[108:109], v[230:231] op_sel_hi:[1,0,1]
	v_pk_fma_f32 v[222:223], v[100:101], v[112:113], v[222:223] op_sel_hi:[1,0,1]
	v_pk_fma_f32 v[230:231], v[102:103], v[112:113], v[230:231] op_sel_hi:[1,0,1]
	v_pk_fma_f32 v[124:125], v[104:105], v[114:115], v[222:223] op_sel_hi:[1,0,1]
	v_pk_fma_f32 v[224:225], v[106:107], v[114:115], v[230:231] op_sel_hi:[1,0,1]
	v_add_u32_e32 v204, s44, v72
	ds_read_b128 v[34:37], v204
	ds_read_b128 v[38:41], v204 offset:16
	ds_read_b128 v[100:103], v204 offset:32
	ds_read_b128 v[104:107], v204 offset:48
	v_lshlrev_b32_e32 v116, 16, v28
	v_and_b32_e32 v118, 0xffff0000, v28
	v_lshlrev_b32_e32 v120, 16, v29
	v_and_b32_e32 v122, 0xffff0000, v29
	s_waitcnt lgkmcnt(4)
	v_pk_mul_f32 v[222:223], v[210:211], v[118:119] op_sel_hi:[1,0]
	v_pk_mul_f32 v[230:231], v[212:213], v[118:119] op_sel_hi:[1,0]
	v_pk_fma_f32 v[222:223], v[206:207], v[116:117], v[222:223] op_sel_hi:[1,0,1]
	v_pk_fma_f32 v[230:231], v[208:209], v[116:117], v[230:231] op_sel_hi:[1,0,1]
	v_pk_fma_f32 v[222:223], v[214:215], v[120:121], v[222:223] op_sel_hi:[1,0,1]
	v_pk_fma_f32 v[230:231], v[216:217], v[120:121], v[230:231] op_sel_hi:[1,0,1]
	v_pk_fma_f32 v[226:227], v[218:219], v[122:123], v[222:223] op_sel_hi:[1,0,1]
	v_pk_fma_f32 v[228:229], v[220:221], v[122:123], v[230:231] op_sel_hi:[1,0,1]
	v_cvt_pk_bf16_f32 v246, v124, v125
	v_cvt_pk_bf16_f32 v247, v224, v225
	v_cvt_pk_bf16_f32 v248, v226, v227
	v_cvt_pk_bf16_f32 v249, v228, v229
	ds_write_b128 v98, v[246:249]
	ds_read_b128 v[206:209], v204 offset:64
	ds_read_b128 v[210:213], v204 offset:80
	ds_read_b128 v[214:217], v204 offset:96
	ds_read_b128 v[218:221], v204 offset:112
	s_waitcnt vmcnt(0)
	v_lshlrev_b32_e32 v108, 16, v30
	v_and_b32_e32 v110, 0xffff0000, v30
	v_lshlrev_b32_e32 v112, 16, v31
	v_and_b32_e32 v114, 0xffff0000, v31
	s_waitcnt lgkmcnt(5)
	v_pk_mul_f32 v[222:223], v[38:39], v[110:111] op_sel_hi:[1,0]
	v_pk_mul_f32 v[230:231], v[40:41], v[110:111] op_sel_hi:[1,0]
	v_pk_fma_f32 v[222:223], v[34:35], v[108:109], v[222:223] op_sel_hi:[1,0,1]
	v_pk_fma_f32 v[230:231], v[36:37], v[108:109], v[230:231] op_sel_hi:[1,0,1]
	v_pk_fma_f32 v[222:223], v[100:101], v[112:113], v[222:223] op_sel_hi:[1,0,1]
	v_pk_fma_f32 v[230:231], v[102:103], v[112:113], v[230:231] op_sel_hi:[1,0,1]
	v_pk_fma_f32 v[124:125], v[104:105], v[114:115], v[222:223] op_sel_hi:[1,0,1]
	v_pk_fma_f32 v[224:225], v[106:107], v[114:115], v[230:231] op_sel_hi:[1,0,1]
	v_lshlrev_b32_e32 v116, 16, v32
	v_and_b32_e32 v118, 0xffff0000, v32
	v_lshlrev_b32_e32 v120, 16, v33
	v_and_b32_e32 v122, 0xffff0000, v33
	s_waitcnt lgkmcnt(0)
	v_pk_mul_f32 v[222:223], v[210:211], v[118:119] op_sel_hi:[1,0]
	v_pk_mul_f32 v[230:231], v[212:213], v[118:119] op_sel_hi:[1,0]
	v_pk_fma_f32 v[222:223], v[206:207], v[116:117], v[222:223] op_sel_hi:[1,0,1]
	v_pk_fma_f32 v[230:231], v[208:209], v[116:117], v[230:231] op_sel_hi:[1,0,1]
	v_pk_fma_f32 v[222:223], v[214:215], v[120:121], v[222:223] op_sel_hi:[1,0,1]
	v_pk_fma_f32 v[230:231], v[216:217], v[120:121], v[230:231] op_sel_hi:[1,0,1]
	v_pk_fma_f32 v[226:227], v[218:219], v[122:123], v[222:223] op_sel_hi:[1,0,1]
	v_pk_fma_f32 v[228:229], v[220:221], v[122:123], v[230:231] op_sel_hi:[1,0,1]
	v_cvt_pk_bf16_f32 v246, v124, v125
	v_cvt_pk_bf16_f32 v247, v224, v225
	v_cvt_pk_bf16_f32 v248, v226, v227
	v_cvt_pk_bf16_f32 v249, v228, v229
	ds_write_b128 v99, v[246:249]
	s_and_saveexec_b64 s[56:57], s[4:5]
	s_cbranch_execz .LBB0_677
	s_lshl_b32 s80, s63, 2
	v_mov_b32_e32 v36, s80
	global_load_dword v37, v36, s[2:3] offset:16
	v_mov_b32_e32 v35, s55
	v_or_b32_e32 v34, s54, v46
	v_lshlrev_b64 v[34:35], 7, v[34:35]
	v_lshl_add_u64 v[34:35], s[48:49], 0, v[34:35]
	v_lshl_add_u64 v[34:35], v[34:35], 0, s[80:81]
	global_load_dword v38, v[34:35], off offset:16
	global_load_dword v39, v[34:35], off offset:48
	global_load_dword v40, v[34:35], off offset:80
	global_load_dword v41, v[34:35], off offset:112
	s_nop 0
	global_load_dword v36, v36, s[2:3]
	s_nop 0
	global_load_dword v57, v[34:35], off offset:96
	global_load_dword v59, v[34:35], off offset:64
	global_load_dword v100, v[34:35], off offset:32
	s_nop 0
	global_load_dword v34, v[34:35], off
	s_waitcnt vmcnt(8)
	v_add_f32_e32 v35, v37, v38
	s_waitcnt vmcnt(7)
	v_add_f32_e32 v35, v35, v39
	s_waitcnt vmcnt(6)
	v_add_f32_e32 v35, v35, v40
	s_waitcnt vmcnt(5)
	v_add_f32_e32 v35, v35, v41
	v_mul_f32_e64 v37, |v35|, s72
	v_exp_f32_e32 v37, v37
	v_add_u32_e32 v38, -1, v234
	v_cmp_lt_i32_e64 s[44:45], v38, v242
	v_max_f32_e64 v35, -v35, 0
	v_add_f32_e32 v37, 1.0, v37
	v_cndmask_b32_e64 v38, v38, v234, s[44:45]
	v_cmp_gt_f32_e64 s[44:45], s71, v37
	v_lshlrev_b32_e32 v38, 2, v38
	s_waitcnt vmcnt(0)
	v_add_f32_e32 v34, v36, v34
	v_cndmask_b32_e64 v39, 0, 32, s[44:45]
	v_ldexp_f32 v37, v37, v39
	v_log_f32_e32 v37, v37
	v_cndmask_b32_e64 v39, 0, v243, s[44:45]
	v_add_f32_e32 v34, v34, v100
	v_add_f32_e32 v34, v34, v59
	v_mul_f32_e32 v40, 0x3f317217, v37
	v_fma_f32 v40, v37, s73, -v40
	v_fmac_f32_e32 v40, 0x3377d1cf, v37
	v_fmac_f32_e32 v40, 0x3f317217, v37
	v_cmp_lt_f32_e64 s[44:45], |v37|, s74
	v_add_f32_e32 v36, v34, v57
	s_nop 0
	v_cndmask_b32_e64 v37, v37, v40, s[44:45]
	v_sub_f32_e32 v37, v37, v39
	v_add_f32_e32 v35, v35, v37
	v_xor_b32_e32 v37, 0x80000000, v35
	ds_bpermute_b32 v37, v38, v37
	v_add_u32_e32 v38, -2, v234
	v_cmp_lt_i32_e64 s[44:45], v38, v242
	s_waitcnt lgkmcnt(0)
	v_sub_f32_e32 v37, v37, v35
	v_cndmask_b32_e64 v38, v38, v234, s[44:45]
	v_lshlrev_b32_e32 v38, 2, v38
	v_cndmask_b32_e64 v35, v37, -v35, s[6:7]
	ds_bpermute_b32 v37, v38, v35
	v_add_u32_e32 v38, -4, v234
	v_cmp_lt_i32_e64 s[44:45], v38, v242
	s_waitcnt lgkmcnt(0)
	v_add_f32_e32 v37, v35, v37
	v_cndmask_b32_e64 v38, v38, v234, s[44:45]
	v_lshlrev_b32_e32 v38, 2, v38
	v_cndmask_b32_e64 v35, v37, v35, s[14:15]
	ds_bpermute_b32 v37, v38, v35
	v_add_u32_e32 v38, -8, v234
	v_cmp_lt_i32_e64 s[44:45], v38, v242
	s_waitcnt lgkmcnt(0)
	v_add_f32_e32 v37, v35, v37
	v_cndmask_b32_e64 v38, v38, v234, s[44:45]
	v_lshlrev_b32_e32 v38, 2, v38
	v_cndmask_b32_e64 v35, v37, v35, s[16:17]
	ds_bpermute_b32 v37, v38, v35
	v_add_u32_e32 v38, -16, v234
	v_cmp_lt_i32_e64 s[44:45], v38, v242
	s_waitcnt lgkmcnt(0)
	v_add_f32_e32 v37, v35, v37
	v_cndmask_b32_e64 v38, v38, v234, s[44:45]
	v_lshlrev_b32_e32 v38, 2, v38
	v_cndmask_b32_e64 v35, v37, v35, s[18:19]
	ds_bpermute_b32 v37, v38, v35
	v_subrev_u32_e32 v38, 32, v234
	v_cmp_lt_i32_e64 s[44:45], v38, v242
	s_waitcnt lgkmcnt(0)
	v_add_f32_e32 v37, v35, v37
	v_cndmask_b32_e64 v38, v38, v234, s[44:45]
	v_lshlrev_b32_e32 v38, 2, v38
	v_cndmask_b32_e64 v35, v37, v35, s[10:11]
	ds_bpermute_b32 v37, v38, v35
	s_waitcnt lgkmcnt(0)
	v_add_f32_e32 v34, v35, v37
	v_cndmask_b32_e64 v35, v34, v35, s[20:21]
	v_lshl_or_b32 v34, v234, 2, v244
	ds_bpermute_b32 v34, v34, v35
	ds_write_b32 v1, v35
	ds_write_b32 v47, v36
	v_mul_f32_e32 v37, 0x3fb8aa3b, v35
	v_exp_f32_e32 v37, v37
	s_waitcnt lgkmcnt(2)
	v_sub_f32_e32 v35, v34, v35
	v_add_f32_e32 v35, v36, v35
	v_mul_f32_e32 v35, 0x3fb8aa3b, v35
	v_exp_f32_e32 v35, v35
	v_lshlrev_b32_e32 v36, 2, v46
	global_store_dword v36, v37, s[50:51]
	v_lshl_add_u64 v[36:37], v[42:43], 2, s[50:51]
	global_store_dword v[36:37], v35, off offset:256
	s_and_b64 exec, exec, s[6:7]
	s_cbranch_execz .LBB0_677
	v_mul_f32_e32 v34, 0x3fb8aa3b, v34
	v_exp_f32_e32 v34, v34
	global_store_dword v0, v34, s[50:51] offset:768
